# GEMM K loops: post-MMA barrier moved up before the last 5 (was 4) MFMAs of each segment
# baseline (speedup 1.0000x reference)
.LBB0_143:
	s_add_u32 s26, s16, 0xfffc0080
	s_addc_u32 s27, s17, -1
	s_add_i32 s34, 0, 0x10000
	s_cmp_eq_u32 s37, 12
	s_cselect_b32 s31, s9, s27
	s_cselect_b32 s30, s25, s26
	v_add_u32_e32 v138, s34, v141
	s_cselect_b32 s27, s7, s36
	s_cselect_b32 s26, s28, s29
	s_add_i32 s40, 0, 0x14000
	ds_read_b128 v[144:147], v138
	ds_read_b128 v[148:151], v138 offset:1024
	ds_read_b128 v[152:155], v138 offset:2048
	ds_read_b128 v[156:159], v138 offset:3072
	v_add_u32_e32 v138, s40, v141
	ds_read_b128 v[160:163], v138
	ds_read_b128 v[164:167], v138 offset:1024
	ds_read_b128 v[168:171], v138 offset:2048
	ds_read_b128 v[172:175], v138 offset:3072
	s_add_i32 m0, s53, 0xc000
	ds_read_b128 v[176:179], v143
	ds_read_b128 v[180:183], v143 offset:1024
	ds_read_b128 v[184:187], v143 offset:2048
	ds_read_b128 v[188:191], v143 offset:3072
	ds_read_b128 v[192:195], v143 offset:4096
	ds_read_b128 v[196:199], v143 offset:5120
	ds_read_b128 v[200:203], v143 offset:6144
	ds_read_b128 v[204:207], v143 offset:7168
	global_load_lds_dwordx4 v132, s[16:17]
	s_add_i32 m0, s53, 0xe000
	s_nop 0
	global_load_lds_dwordx4 v134, s[16:17]
	s_waitcnt vmcnt(8)
	s_waitcnt lgkmcnt(0)
	s_barrier
	s_setprio 1
	s_waitcnt lgkmcnt(0)
	v_mfma_f32_16x16x32_bf16 v[126:129], v[144:147], v[176:179], v[126:129]
	v_mfma_f32_16x16x32_bf16 v[126:129], v[148:151], v[180:183], v[126:129]
	v_mfma_f32_16x16x32_bf16 v[118:121], v[152:155], v[176:179], v[118:121]
	v_mfma_f32_16x16x32_bf16 v[118:121], v[156:159], v[180:183], v[118:121]
	v_mfma_f32_16x16x32_bf16 v[110:113], v[144:147], v[184:187], v[110:113]
	v_mfma_f32_16x16x32_bf16 v[110:113], v[148:151], v[188:191], v[110:113]
	v_mfma_f32_16x16x32_bf16 v[102:105], v[152:155], v[184:187], v[102:105]
	v_mfma_f32_16x16x32_bf16 v[102:105], v[156:159], v[188:191], v[102:105]
	v_mfma_f32_16x16x32_bf16 v[94:97], v[144:147], v[192:195], v[94:97]
	v_mfma_f32_16x16x32_bf16 v[94:97], v[148:151], v[196:199], v[94:97]
	v_mfma_f32_16x16x32_bf16 v[86:89], v[152:155], v[192:195], v[86:89]
	v_mfma_f32_16x16x32_bf16 v[86:89], v[156:159], v[196:199], v[86:89]
	v_mfma_f32_16x16x32_bf16 v[78:81], v[144:147], v[200:203], v[78:81]
	v_mfma_f32_16x16x32_bf16 v[78:81], v[148:151], v[204:207], v[78:81]
	v_mfma_f32_16x16x32_bf16 v[70:73], v[152:155], v[200:203], v[70:73]
	v_mfma_f32_16x16x32_bf16 v[70:73], v[156:159], v[204:207], v[70:73]
	s_setprio 0
	s_setprio 1
	v_mfma_f32_16x16x32_bf16 v[122:125], v[160:163], v[176:179], v[122:125]
	v_mfma_f32_16x16x32_bf16 v[122:125], v[164:167], v[180:183], v[122:125]
	v_mfma_f32_16x16x32_bf16 v[114:117], v[168:171], v[176:179], v[114:117]
	v_mfma_f32_16x16x32_bf16 v[114:117], v[172:175], v[180:183], v[114:117]
	v_mfma_f32_16x16x32_bf16 v[106:109], v[160:163], v[184:187], v[106:109]
	v_mfma_f32_16x16x32_bf16 v[106:109], v[164:167], v[188:191], v[106:109]
	v_mfma_f32_16x16x32_bf16 v[98:101], v[168:171], v[184:187], v[98:101]
	v_mfma_f32_16x16x32_bf16 v[98:101], v[172:175], v[188:191], v[98:101]
	v_mfma_f32_16x16x32_bf16 v[90:93], v[160:163], v[192:195], v[90:93]
	v_mfma_f32_16x16x32_bf16 v[90:93], v[164:167], v[196:199], v[90:93]
	v_mfma_f32_16x16x32_bf16 v[82:85], v[168:171], v[192:195], v[82:85]
	s_setprio 3
	s_barrier
	v_mfma_f32_16x16x32_bf16 v[82:85], v[172:175], v[196:199], v[82:85]
	v_mfma_f32_16x16x32_bf16 v[74:77], v[160:163], v[200:203], v[74:77]
	v_mfma_f32_16x16x32_bf16 v[74:77], v[164:167], v[204:207], v[74:77]
	v_mfma_f32_16x16x32_bf16 v[66:69], v[168:171], v[200:203], v[66:69]
	v_mfma_f32_16x16x32_bf16 v[66:69], v[172:175], v[204:207], v[66:69]
	s_setprio 0
	s_add_i32 s34, s34, s47
	s_mov_b32 m0, s34
	ds_read_b128 v[176:179], v143 offset:16384
	ds_read_b128 v[180:183], v143 offset:17408
	ds_read_b128 v[184:187], v143 offset:18432
	ds_read_b128 v[188:191], v143 offset:19456
	ds_read_b128 v[192:195], v143 offset:20480
	ds_read_b128 v[196:199], v143 offset:21504
	ds_read_b128 v[200:203], v143 offset:22528
	ds_read_b128 v[204:207], v143 offset:23552
	global_load_lds_dwordx4 v0, s[26:27]
	s_add_i32 m0, s34, 0x2000
	s_add_u32 s34, s26, 0x40000
	s_addc_u32 s35, s27, 0
	s_add_i32 s40, s40, s47
	global_load_lds_dwordx4 v130, s[26:27]
	s_mov_b32 m0, s40
	s_nop 0
	global_load_lds_dwordx4 v0, s[34:35]
	s_add_i32 m0, s40, 0x2000
	s_nop 0
	global_load_lds_dwordx4 v130, s[34:35]
	s_add_u32 s100, s30, s22
	s_addc_u32 s101, s31, s23
	s_mov_b32 m0, s53
	s_nop 0
	global_load_lds_dwordx4 v0, s[30:31]
	s_mov_b32 m0, s64
	s_nop 0
	global_load_lds_dwordx4 v130, s[30:31]
	s_waitcnt vmcnt(8)
	s_waitcnt lgkmcnt(0)
	s_barrier
	s_setprio 1
	s_waitcnt lgkmcnt(0)
	v_mfma_f32_16x16x32_bf16 v[62:65], v[144:147], v[176:179], v[62:65]
	v_mfma_f32_16x16x32_bf16 v[62:65], v[148:151], v[180:183], v[62:65]
	v_mfma_f32_16x16x32_bf16 v[54:57], v[152:155], v[176:179], v[54:57]
	v_mfma_f32_16x16x32_bf16 v[54:57], v[156:159], v[180:183], v[54:57]
	v_mfma_f32_16x16x32_bf16 v[46:49], v[144:147], v[184:187], v[46:49]
	v_mfma_f32_16x16x32_bf16 v[46:49], v[148:151], v[188:191], v[46:49]
	v_mfma_f32_16x16x32_bf16 v[38:41], v[152:155], v[184:187], v[38:41]
	v_mfma_f32_16x16x32_bf16 v[38:41], v[156:159], v[188:191], v[38:41]
	v_mfma_f32_16x16x32_bf16 v[30:33], v[144:147], v[192:195], v[30:33]
	v_mfma_f32_16x16x32_bf16 v[30:33], v[148:151], v[196:199], v[30:33]
	v_mfma_f32_16x16x32_bf16 v[22:25], v[152:155], v[192:195], v[22:25]
	v_mfma_f32_16x16x32_bf16 v[22:25], v[156:159], v[196:199], v[22:25]
	v_mfma_f32_16x16x32_bf16 v[14:17], v[144:147], v[200:203], v[14:17]
	v_mfma_f32_16x16x32_bf16 v[14:17], v[148:151], v[204:207], v[14:17]
	v_mfma_f32_16x16x32_bf16 v[6:9], v[152:155], v[200:203], v[6:9]
	v_mfma_f32_16x16x32_bf16 v[6:9], v[156:159], v[204:207], v[6:9]
	s_setprio 0
	s_setprio 1
	v_mfma_f32_16x16x32_bf16 v[58:61], v[160:163], v[176:179], v[58:61]
	v_mfma_f32_16x16x32_bf16 v[58:61], v[164:167], v[180:183], v[58:61]
	v_mfma_f32_16x16x32_bf16 v[50:53], v[168:171], v[176:179], v[50:53]
	v_mfma_f32_16x16x32_bf16 v[50:53], v[172:175], v[180:183], v[50:53]
	v_mfma_f32_16x16x32_bf16 v[42:45], v[160:163], v[184:187], v[42:45]
	v_mfma_f32_16x16x32_bf16 v[42:45], v[164:167], v[188:191], v[42:45]
	v_mfma_f32_16x16x32_bf16 v[34:37], v[168:171], v[184:187], v[34:37]
	v_mfma_f32_16x16x32_bf16 v[34:37], v[172:175], v[188:191], v[34:37]
	v_mfma_f32_16x16x32_bf16 v[26:29], v[160:163], v[192:195], v[26:29]
	v_mfma_f32_16x16x32_bf16 v[26:29], v[164:167], v[196:199], v[26:29]
	v_mfma_f32_16x16x32_bf16 v[18:21], v[168:171], v[192:195], v[18:21]
	s_setprio 3
	s_barrier
	v_mfma_f32_16x16x32_bf16 v[18:21], v[172:175], v[196:199], v[18:21]
	v_mfma_f32_16x16x32_bf16 v[10:13], v[160:163], v[200:203], v[10:13]
	v_mfma_f32_16x16x32_bf16 v[10:13], v[164:167], v[204:207], v[10:13]
	v_mfma_f32_16x16x32_bf16 v[2:5], v[168:171], v[200:203], v[2:5]
	v_mfma_f32_16x16x32_bf16 v[2:5], v[172:175], v[204:207], v[2:5]
	s_setprio 0
	s_add_i32 s34, 0, 0x18000
	s_add_i32 s35, 0, 0x1c000
	v_add_u32_e32 v156, s34, v141
	v_add_u32_e32 v172, s35, v141
	ds_read_b128 v[144:147], v156
	ds_read_b128 v[148:151], v156 offset:1024
	ds_read_b128 v[152:155], v156 offset:2048
	ds_read_b128 v[156:159], v156 offset:3072
	ds_read_b128 v[160:163], v172
	ds_read_b128 v[164:167], v172 offset:1024
	ds_read_b128 v[168:171], v172 offset:2048
	ds_read_b128 v[172:175], v172 offset:3072
	s_add_u32 s30, s30, 0x40000
	s_addc_u32 s31, s31, 0
	s_mov_b32 m0, s65
	ds_read_b128 v[176:179], v143 offset:32768
	ds_read_b128 v[180:183], v143 offset:33792
	ds_read_b128 v[184:187], v143 offset:34816
	ds_read_b128 v[188:191], v143 offset:35840
	ds_read_b128 v[192:195], v143 offset:36864
	ds_read_b128 v[196:199], v143 offset:37888
	ds_read_b128 v[200:203], v143 offset:38912
	ds_read_b128 v[204:207], v143 offset:39936
	global_load_lds_dwordx4 v0, s[30:31]
	s_mov_b32 m0, s68
	s_nop 0
	global_load_lds_dwordx4 v130, s[30:31]
	s_waitcnt vmcnt(8)
	s_waitcnt lgkmcnt(0)
	s_barrier
	s_setprio 1
	s_waitcnt lgkmcnt(0)
	v_mfma_f32_16x16x32_bf16 v[126:129], v[144:147], v[176:179], v[126:129]
	v_mfma_f32_16x16x32_bf16 v[126:129], v[148:151], v[180:183], v[126:129]
	v_mfma_f32_16x16x32_bf16 v[118:121], v[152:155], v[176:179], v[118:121]
	v_mfma_f32_16x16x32_bf16 v[118:121], v[156:159], v[180:183], v[118:121]
	v_mfma_f32_16x16x32_bf16 v[110:113], v[144:147], v[184:187], v[110:113]
	v_mfma_f32_16x16x32_bf16 v[110:113], v[148:151], v[188:191], v[110:113]
	v_mfma_f32_16x16x32_bf16 v[102:105], v[152:155], v[184:187], v[102:105]
	v_mfma_f32_16x16x32_bf16 v[102:105], v[156:159], v[188:191], v[102:105]
	v_mfma_f32_16x16x32_bf16 v[94:97], v[144:147], v[192:195], v[94:97]
	v_mfma_f32_16x16x32_bf16 v[94:97], v[148:151], v[196:199], v[94:97]
	v_mfma_f32_16x16x32_bf16 v[86:89], v[152:155], v[192:195], v[86:89]
	v_mfma_f32_16x16x32_bf16 v[86:89], v[156:159], v[196:199], v[86:89]
	v_mfma_f32_16x16x32_bf16 v[78:81], v[144:147], v[200:203], v[78:81]
	v_mfma_f32_16x16x32_bf16 v[78:81], v[148:151], v[204:207], v[78:81]
	v_mfma_f32_16x16x32_bf16 v[70:73], v[152:155], v[200:203], v[70:73]
	v_mfma_f32_16x16x32_bf16 v[70:73], v[156:159], v[204:207], v[70:73]
	s_setprio 0
	s_setprio 1
	v_mfma_f32_16x16x32_bf16 v[122:125], v[160:163], v[176:179], v[122:125]
	v_mfma_f32_16x16x32_bf16 v[122:125], v[164:167], v[180:183], v[122:125]
	v_mfma_f32_16x16x32_bf16 v[114:117], v[168:171], v[176:179], v[114:117]
	v_mfma_f32_16x16x32_bf16 v[114:117], v[172:175], v[180:183], v[114:117]
	v_mfma_f32_16x16x32_bf16 v[106:109], v[160:163], v[184:187], v[106:109]
	v_mfma_f32_16x16x32_bf16 v[106:109], v[164:167], v[188:191], v[106:109]
	v_mfma_f32_16x16x32_bf16 v[98:101], v[168:171], v[184:187], v[98:101]
	v_mfma_f32_16x16x32_bf16 v[98:101], v[172:175], v[188:191], v[98:101]
	v_mfma_f32_16x16x32_bf16 v[90:93], v[160:163], v[192:195], v[90:93]
	v_mfma_f32_16x16x32_bf16 v[90:93], v[164:167], v[196:199], v[90:93]
	v_mfma_f32_16x16x32_bf16 v[82:85], v[168:171], v[192:195], v[82:85]
	s_setprio 3
	s_barrier
	v_mfma_f32_16x16x32_bf16 v[82:85], v[172:175], v[196:199], v[82:85]
	v_mfma_f32_16x16x32_bf16 v[74:77], v[160:163], v[200:203], v[74:77]
	v_mfma_f32_16x16x32_bf16 v[74:77], v[164:167], v[204:207], v[74:77]
	v_mfma_f32_16x16x32_bf16 v[66:69], v[168:171], v[200:203], v[66:69]
	v_mfma_f32_16x16x32_bf16 v[66:69], v[172:175], v[204:207], v[66:69]
	s_setprio 0
	s_add_i32 s30, s34, s47
	s_add_u32 s98, s26, s22
	s_addc_u32 s99, s27, s23
	s_mov_b32 m0, s30
	ds_read_b128 v[176:179], v143 offset:49152
	ds_read_b128 v[180:183], v143 offset:50176
	ds_read_b128 v[184:187], v143 offset:51200
	ds_read_b128 v[188:191], v143 offset:52224
	ds_read_b128 v[192:195], v143 offset:53248
	ds_read_b128 v[196:199], v143 offset:54272
	ds_read_b128 v[200:203], v143 offset:55296
	ds_read_b128 v[204:207], v143 offset:56320
	global_load_lds_dwordx4 v0, s[98:99]
	s_add_i32 m0, s30, 0x2000
	s_add_u32 s26, s26, 0x40080
	s_addc_u32 s27, s27, 0
	s_add_i32 s30, s35, s47
	global_load_lds_dwordx4 v130, s[98:99]
	s_mov_b32 m0, s30
	s_nop 0
	global_load_lds_dwordx4 v0, s[26:27]
	s_add_i32 m0, s30, 0x2000
	s_nop 0
	global_load_lds_dwordx4 v130, s[26:27]
	s_mov_b32 m0, s69
	s_nop 0
	global_load_lds_dwordx4 v0, s[100:101]
	s_mov_b32 m0, s70
	s_nop 0
	global_load_lds_dwordx4 v130, s[100:101]
	s_waitcnt vmcnt(8)
	s_waitcnt lgkmcnt(0)
	s_barrier
	s_setprio 1
	s_waitcnt lgkmcnt(0)
	v_mfma_f32_16x16x32_bf16 v[62:65], v[144:147], v[176:179], v[62:65]
	v_mfma_f32_16x16x32_bf16 v[62:65], v[148:151], v[180:183], v[62:65]
	v_mfma_f32_16x16x32_bf16 v[54:57], v[152:155], v[176:179], v[54:57]
	v_mfma_f32_16x16x32_bf16 v[54:57], v[156:159], v[180:183], v[54:57]
	v_mfma_f32_16x16x32_bf16 v[46:49], v[144:147], v[184:187], v[46:49]
	v_mfma_f32_16x16x32_bf16 v[46:49], v[148:151], v[188:191], v[46:49]
	v_mfma_f32_16x16x32_bf16 v[38:41], v[152:155], v[184:187], v[38:41]
	v_mfma_f32_16x16x32_bf16 v[38:41], v[156:159], v[188:191], v[38:41]
	v_mfma_f32_16x16x32_bf16 v[30:33], v[144:147], v[192:195], v[30:33]
	v_mfma_f32_16x16x32_bf16 v[30:33], v[148:151], v[196:199], v[30:33]
	v_mfma_f32_16x16x32_bf16 v[22:25], v[152:155], v[192:195], v[22:25]
	v_mfma_f32_16x16x32_bf16 v[22:25], v[156:159], v[196:199], v[22:25]
	v_mfma_f32_16x16x32_bf16 v[14:17], v[144:147], v[200:203], v[14:17]
	v_mfma_f32_16x16x32_bf16 v[14:17], v[148:151], v[204:207], v[14:17]
	v_mfma_f32_16x16x32_bf16 v[6:9], v[152:155], v[200:203], v[6:9]
	v_mfma_f32_16x16x32_bf16 v[6:9], v[156:159], v[204:207], v[6:9]
	s_setprio 0
	s_setprio 1
	v_mfma_f32_16x16x32_bf16 v[58:61], v[160:163], v[176:179], v[58:61]
	v_mfma_f32_16x16x32_bf16 v[58:61], v[164:167], v[180:183], v[58:61]
	v_mfma_f32_16x16x32_bf16 v[50:53], v[168:171], v[176:179], v[50:53]
	v_mfma_f32_16x16x32_bf16 v[50:53], v[172:175], v[180:183], v[50:53]
	v_mfma_f32_16x16x32_bf16 v[42:45], v[160:163], v[184:187], v[42:45]
	v_mfma_f32_16x16x32_bf16 v[42:45], v[164:167], v[188:191], v[42:45]
	v_mfma_f32_16x16x32_bf16 v[34:37], v[168:171], v[184:187], v[34:37]
	v_mfma_f32_16x16x32_bf16 v[34:37], v[172:175], v[188:191], v[34:37]
	v_mfma_f32_16x16x32_bf16 v[26:29], v[160:163], v[192:195], v[26:29]
	v_mfma_f32_16x16x32_bf16 v[26:29], v[164:167], v[196:199], v[26:29]
	v_mfma_f32_16x16x32_bf16 v[18:21], v[168:171], v[192:195], v[18:21]
	s_setprio 3
	s_barrier
	v_mfma_f32_16x16x32_bf16 v[18:21], v[172:175], v[196:199], v[18:21]
	v_mfma_f32_16x16x32_bf16 v[10:13], v[160:163], v[200:203], v[10:13]
	v_mfma_f32_16x16x32_bf16 v[10:13], v[164:167], v[204:207], v[10:13]
	v_mfma_f32_16x16x32_bf16 v[2:5], v[168:171], v[200:203], v[2:5]
	v_mfma_f32_16x16x32_bf16 v[2:5], v[172:175], v[204:207], v[2:5]
	s_setprio 0
	s_add_i32 s37, s37, 2
	s_add_u32 s16, s16, 0x100
	s_addc_u32 s17, s17, 0
	s_add_u32 s29, s29, 0x100
	s_addc_u32 s36, s36, 0
	s_cmp_gt_u32 s37, 13
	s_cbranch_scc0 .LBB0_143
	s_and_b64 vcc, exec, s[2:3]
	s_cbranch_vccz .LBB0_146
	s_barrier

.LBB0_233:
	s_add_u32 s4, s0, 0xfffc0080
	s_addc_u32 s5, s1, -1
	s_add_i32 s18, 0, 0x10000
	s_cmp_eq_u32 s17, 12
	s_cselect_b32 s9, s3, s5
	s_cselect_b32 s8, s11, s4
	v_add_u32_e32 v0, s18, v191
	s_cselect_b32 s5, s12, s15
	s_cselect_b32 s4, s13, s14
	s_add_i32 s25, 0, 0x14000
	ds_read_b128 v[2:5], v0
	ds_read_b128 v[6:9], v0 offset:1024
	ds_read_b128 v[10:13], v0 offset:2048
	ds_read_b128 v[14:17], v0 offset:3072
	v_add_u32_e32 v0, s25, v191
	ds_read_b128 v[146:149], v0
	ds_read_b128 v[150:153], v0 offset:1024
	ds_read_b128 v[154:157], v0 offset:2048
	ds_read_b128 v[158:161], v0 offset:3072
	s_add_i32 m0, s65, 0xc000
	ds_read_b128 v[162:165], v200
	ds_read_b128 v[166:169], v200 offset:1024
	ds_read_b128 v[182:185], v200 offset:2048
	ds_read_b128 v[186:189], v200 offset:3072
	ds_read_b128 v[202:205], v200 offset:4096
	ds_read_b128 v[206:209], v200 offset:5120
	ds_read_b128 v[222:225], v200 offset:6144
	ds_read_b128 v[226:229], v200 offset:7168
	global_load_lds_dwordx4 v178, s[0:1]
	s_add_i32 m0, s65, 0xe000
	s_nop 0
	global_load_lds_dwordx4 v180, s[0:1]
	s_waitcnt vmcnt(8)
	s_waitcnt lgkmcnt(0)
	s_barrier
	s_setprio 1
	s_waitcnt lgkmcnt(0)
	v_mfma_f32_16x16x32_bf16 v[142:145], v[2:5], v[162:165], v[142:145]
	v_mfma_f32_16x16x32_bf16 v[142:145], v[6:9], v[166:169], v[142:145]
	v_mfma_f32_16x16x32_bf16 v[138:141], v[10:13], v[162:165], v[138:141]
	v_mfma_f32_16x16x32_bf16 v[138:141], v[14:17], v[166:169], v[138:141]
	v_mfma_f32_16x16x32_bf16 v[134:137], v[2:5], v[182:185], v[134:137]
	v_mfma_f32_16x16x32_bf16 v[134:137], v[6:9], v[186:189], v[134:137]
	v_mfma_f32_16x16x32_bf16 v[126:129], v[10:13], v[182:185], v[126:129]
	v_mfma_f32_16x16x32_bf16 v[126:129], v[14:17], v[186:189], v[126:129]
	v_mfma_f32_16x16x32_bf16 v[118:121], v[2:5], v[202:205], v[118:121]
	v_mfma_f32_16x16x32_bf16 v[118:121], v[6:9], v[206:209], v[118:121]
	v_mfma_f32_16x16x32_bf16 v[110:113], v[10:13], v[202:205], v[110:113]
	v_mfma_f32_16x16x32_bf16 v[110:113], v[14:17], v[206:209], v[110:113]
	v_mfma_f32_16x16x32_bf16 v[102:105], v[2:5], v[222:225], v[102:105]
	v_mfma_f32_16x16x32_bf16 v[102:105], v[6:9], v[226:229], v[102:105]
	v_mfma_f32_16x16x32_bf16 v[94:97], v[10:13], v[222:225], v[94:97]
	v_mfma_f32_16x16x32_bf16 v[94:97], v[14:17], v[226:229], v[94:97]
	s_setprio 0
	s_setprio 1
	v_mfma_f32_16x16x32_bf16 v[130:133], v[146:149], v[162:165], v[130:133]
	v_mfma_f32_16x16x32_bf16 v[130:133], v[150:153], v[166:169], v[130:133]
	v_mfma_f32_16x16x32_bf16 v[122:125], v[154:157], v[162:165], v[122:125]
	v_mfma_f32_16x16x32_bf16 v[122:125], v[158:161], v[166:169], v[122:125]
	v_mfma_f32_16x16x32_bf16 v[114:117], v[146:149], v[182:185], v[114:117]
	v_mfma_f32_16x16x32_bf16 v[114:117], v[150:153], v[186:189], v[114:117]
	v_mfma_f32_16x16x32_bf16 v[106:109], v[154:157], v[182:185], v[106:109]
	v_mfma_f32_16x16x32_bf16 v[106:109], v[158:161], v[186:189], v[106:109]
	v_mfma_f32_16x16x32_bf16 v[98:101], v[146:149], v[202:205], v[98:101]
	v_mfma_f32_16x16x32_bf16 v[98:101], v[150:153], v[206:209], v[98:101]
	v_mfma_f32_16x16x32_bf16 v[90:93], v[154:157], v[202:205], v[90:93]
	s_setprio 3
	s_barrier
	v_mfma_f32_16x16x32_bf16 v[90:93], v[158:161], v[206:209], v[90:93]
	v_mfma_f32_16x16x32_bf16 v[86:89], v[146:149], v[222:225], v[86:89]
	v_mfma_f32_16x16x32_bf16 v[86:89], v[150:153], v[226:229], v[86:89]
	v_mfma_f32_16x16x32_bf16 v[82:85], v[154:157], v[222:225], v[82:85]
	v_mfma_f32_16x16x32_bf16 v[82:85], v[158:161], v[226:229], v[82:85]
	s_setprio 0
	s_add_i32 s18, s18, s64
	s_mov_b32 m0, s18
	ds_read_b128 v[162:165], v200 offset:16384
	ds_read_b128 v[166:169], v200 offset:17408
	ds_read_b128 v[182:185], v200 offset:18432
	ds_read_b128 v[186:189], v200 offset:19456
	ds_read_b128 v[202:205], v200 offset:20480
	ds_read_b128 v[206:209], v200 offset:21504
	ds_read_b128 v[222:225], v200 offset:22528
	ds_read_b128 v[226:229], v200 offset:23552
	global_load_lds_dwordx4 v172, s[4:5]
	s_add_i32 m0, s18, 0x2000
	s_add_u32 s18, s4, 0x40000
	s_addc_u32 s19, s5, 0
	s_add_i32 s25, s25, s64
	global_load_lds_dwordx4 v170, s[4:5]
	s_mov_b32 m0, s25
	s_nop 0
	global_load_lds_dwordx4 v172, s[18:19]
	s_add_i32 m0, s25, 0x2000
	s_nop 0
	global_load_lds_dwordx4 v170, s[18:19]
	s_add_u32 s100, s8, s22
	s_addc_u32 s101, s9, s23
	s_mov_b32 m0, s65
	s_nop 0
	global_load_lds_dwordx4 v172, s[8:9]
	s_mov_b32 m0, s68
	s_nop 0
	global_load_lds_dwordx4 v170, s[8:9]
	s_waitcnt vmcnt(8)
	s_waitcnt lgkmcnt(0)
	s_barrier
	s_setprio 1
	s_waitcnt lgkmcnt(0)
	v_mfma_f32_16x16x32_bf16 v[78:81], v[2:5], v[162:165], v[78:81]
	v_mfma_f32_16x16x32_bf16 v[74:77], v[10:13], v[162:165], v[74:77]
	v_mfma_f32_16x16x32_bf16 v[70:73], v[2:5], v[182:185], v[70:73]
	v_mfma_f32_16x16x32_bf16 v[62:65], v[10:13], v[182:185], v[62:65]
	v_mfma_f32_16x16x32_bf16 v[54:57], v[2:5], v[202:205], v[54:57]
	v_mfma_f32_16x16x32_bf16 v[46:49], v[10:13], v[202:205], v[46:49]
	v_mfma_f32_16x16x32_bf16 v[2:5], v[2:5], v[222:225], v[38:41]
	v_mfma_f32_16x16x32_bf16 v[78:81], v[6:9], v[166:169], v[78:81]
	v_mfma_f32_16x16x32_bf16 v[74:77], v[14:17], v[166:169], v[74:77]
	v_mfma_f32_16x16x32_bf16 v[70:73], v[6:9], v[186:189], v[70:73]
	v_mfma_f32_16x16x32_bf16 v[62:65], v[14:17], v[186:189], v[62:65]
	v_mfma_f32_16x16x32_bf16 v[54:57], v[6:9], v[206:209], v[54:57]
	v_mfma_f32_16x16x32_bf16 v[46:49], v[14:17], v[206:209], v[46:49]
	v_mfma_f32_16x16x32_bf16 v[2:5], v[6:9], v[226:229], v[2:5]
	v_mfma_f32_16x16x32_bf16 v[6:9], v[10:13], v[222:225], v[30:33]
	v_mfma_f32_16x16x32_bf16 v[6:9], v[14:17], v[226:229], v[6:9]
	s_setprio 0
	s_setprio 1
	v_mfma_f32_16x16x32_bf16 v[30:33], v[146:149], v[182:185], v[50:53]
	v_mfma_f32_16x16x32_bf16 v[50:53], v[150:153], v[186:189], v[30:33]
	v_mfma_f32_16x16x32_bf16 v[30:33], v[154:157], v[182:185], v[42:45]
	v_mfma_f32_16x16x32_bf16 v[42:45], v[158:161], v[186:189], v[30:33]
	v_mfma_f32_16x16x32_bf16 v[30:33], v[146:149], v[202:205], v[34:37]
	v_mfma_f32_16x16x32_bf16 v[26:29], v[154:157], v[202:205], v[26:29]
	v_mfma_f32_16x16x32_bf16 v[22:25], v[146:149], v[222:225], v[22:25]
	v_mfma_f32_16x16x32_bf16 v[18:21], v[154:157], v[222:225], v[18:21]
	v_mfma_f32_16x16x32_bf16 v[10:13], v[146:149], v[162:165], v[66:69]
	v_mfma_f32_16x16x32_bf16 v[14:17], v[154:157], v[162:165], v[58:61]
	v_mfma_f32_16x16x32_bf16 v[34:37], v[150:153], v[206:209], v[30:33]
	s_setprio 3
	s_barrier
	v_mfma_f32_16x16x32_bf16 v[26:29], v[158:161], v[206:209], v[26:29]
	v_mfma_f32_16x16x32_bf16 v[22:25], v[150:153], v[226:229], v[22:25]
	v_mfma_f32_16x16x32_bf16 v[18:21], v[158:161], v[226:229], v[18:21]
	v_mfma_f32_16x16x32_bf16 v[10:13], v[150:153], v[166:169], v[10:13]
	v_mfma_f32_16x16x32_bf16 v[14:17], v[158:161], v[166:169], v[14:17]
	s_setprio 0
	s_add_i32 s18, 0, 0x18000
	v_add_u32_e32 v0, s18, v191
	s_add_i32 s19, 0, 0x1c000
	ds_read_b128 v[30:33], v0
	ds_read_b128 v[38:41], v0 offset:1024
	ds_read_b128 v[58:61], v0 offset:2048
	ds_read_b128 v[66:69], v0 offset:3072
	v_add_u32_e32 v0, s19, v191
	ds_read_b128 v[146:149], v0
	ds_read_b128 v[150:153], v0 offset:1024
	ds_read_b128 v[154:157], v0 offset:2048
	ds_read_b128 v[158:161], v0 offset:3072
	s_add_u32 s8, s8, 0x40000
	s_addc_u32 s9, s9, 0
	s_mov_b32 m0, s69
	ds_read_b128 v[162:165], v200 offset:32768
	ds_read_b128 v[166:169], v200 offset:33792
	ds_read_b128 v[182:185], v200 offset:34816
	ds_read_b128 v[186:189], v200 offset:35840
	ds_read_b128 v[202:205], v200 offset:36864
	ds_read_b128 v[206:209], v200 offset:37888
	ds_read_b128 v[222:225], v200 offset:38912
	ds_read_b128 v[226:229], v200 offset:39936
	global_load_lds_dwordx4 v172, s[8:9]
	s_mov_b32 m0, s70
	s_nop 0
	global_load_lds_dwordx4 v170, s[8:9]
	s_waitcnt vmcnt(8)
	s_waitcnt lgkmcnt(0)
	s_barrier
	s_setprio 1
	s_waitcnt lgkmcnt(0)
	v_mfma_f32_16x16x32_bf16 v[142:145], v[30:33], v[162:165], v[142:145]
	v_mfma_f32_16x16x32_bf16 v[142:145], v[38:41], v[166:169], v[142:145]
	v_mfma_f32_16x16x32_bf16 v[138:141], v[58:61], v[162:165], v[138:141]
	v_mfma_f32_16x16x32_bf16 v[138:141], v[66:69], v[166:169], v[138:141]
	v_mfma_f32_16x16x32_bf16 v[134:137], v[30:33], v[182:185], v[134:137]
	v_mfma_f32_16x16x32_bf16 v[134:137], v[38:41], v[186:189], v[134:137]
	v_mfma_f32_16x16x32_bf16 v[126:129], v[58:61], v[182:185], v[126:129]
	v_mfma_f32_16x16x32_bf16 v[126:129], v[66:69], v[186:189], v[126:129]
	v_mfma_f32_16x16x32_bf16 v[118:121], v[30:33], v[202:205], v[118:121]
	v_mfma_f32_16x16x32_bf16 v[118:121], v[38:41], v[206:209], v[118:121]
	v_mfma_f32_16x16x32_bf16 v[110:113], v[58:61], v[202:205], v[110:113]
	v_mfma_f32_16x16x32_bf16 v[110:113], v[66:69], v[206:209], v[110:113]
	v_mfma_f32_16x16x32_bf16 v[102:105], v[30:33], v[222:225], v[102:105]
	v_mfma_f32_16x16x32_bf16 v[102:105], v[38:41], v[226:229], v[102:105]
	v_mfma_f32_16x16x32_bf16 v[94:97], v[58:61], v[222:225], v[94:97]
	v_mfma_f32_16x16x32_bf16 v[94:97], v[66:69], v[226:229], v[94:97]
	s_setprio 0
	s_setprio 1
	v_mfma_f32_16x16x32_bf16 v[130:133], v[146:149], v[162:165], v[130:133]
	v_mfma_f32_16x16x32_bf16 v[130:133], v[150:153], v[166:169], v[130:133]
	v_mfma_f32_16x16x32_bf16 v[122:125], v[154:157], v[162:165], v[122:125]
	v_mfma_f32_16x16x32_bf16 v[122:125], v[158:161], v[166:169], v[122:125]
	v_mfma_f32_16x16x32_bf16 v[114:117], v[146:149], v[182:185], v[114:117]
	v_mfma_f32_16x16x32_bf16 v[114:117], v[150:153], v[186:189], v[114:117]
	v_mfma_f32_16x16x32_bf16 v[106:109], v[154:157], v[182:185], v[106:109]
	v_mfma_f32_16x16x32_bf16 v[106:109], v[158:161], v[186:189], v[106:109]
	v_mfma_f32_16x16x32_bf16 v[98:101], v[146:149], v[202:205], v[98:101]
	v_mfma_f32_16x16x32_bf16 v[98:101], v[150:153], v[206:209], v[98:101]
	v_mfma_f32_16x16x32_bf16 v[90:93], v[154:157], v[202:205], v[90:93]
	s_setprio 3
	s_barrier
	v_mfma_f32_16x16x32_bf16 v[90:93], v[158:161], v[206:209], v[90:93]
	v_mfma_f32_16x16x32_bf16 v[86:89], v[146:149], v[222:225], v[86:89]
	v_mfma_f32_16x16x32_bf16 v[86:89], v[150:153], v[226:229], v[86:89]
	v_mfma_f32_16x16x32_bf16 v[82:85], v[154:157], v[222:225], v[82:85]
	v_mfma_f32_16x16x32_bf16 v[82:85], v[158:161], v[226:229], v[82:85]
	s_setprio 0
	s_add_i32 s8, s18, s64
	s_add_u32 s98, s4, s22
	s_addc_u32 s99, s5, s23
	s_mov_b32 m0, s8
	ds_read_b128 v[162:165], v200 offset:49152
	ds_read_b128 v[166:169], v200 offset:50176
	ds_read_b128 v[182:185], v200 offset:51200
	ds_read_b128 v[186:189], v200 offset:52224
	ds_read_b128 v[202:205], v200 offset:53248
	ds_read_b128 v[206:209], v200 offset:54272
	ds_read_b128 v[222:225], v200 offset:55296
	ds_read_b128 v[226:229], v200 offset:56320
	global_load_lds_dwordx4 v172, s[98:99]
	s_add_i32 m0, s8, 0x2000
	s_add_u32 s4, s4, 0x40080
	s_addc_u32 s5, s5, 0
	s_add_i32 s8, s19, s64
	global_load_lds_dwordx4 v170, s[98:99]
	s_mov_b32 m0, s8
	s_nop 0
	global_load_lds_dwordx4 v172, s[4:5]
	s_add_i32 m0, s8, 0x2000
	s_nop 0
	global_load_lds_dwordx4 v170, s[4:5]
	s_mov_b32 m0, s94
	s_nop 0
	global_load_lds_dwordx4 v172, s[100:101]
	s_mov_b32 m0, s95
	s_nop 0
	global_load_lds_dwordx4 v170, s[100:101]
	s_waitcnt vmcnt(8)
	s_waitcnt lgkmcnt(0)
	s_barrier
	s_setprio 1
	s_waitcnt lgkmcnt(0)
	v_mfma_f32_16x16x32_bf16 v[78:81], v[30:33], v[162:165], v[78:81]
	v_mfma_f32_16x16x32_bf16 v[70:73], v[30:33], v[182:185], v[70:73]
	v_mfma_f32_16x16x32_bf16 v[54:57], v[30:33], v[202:205], v[54:57]
	v_mfma_f32_16x16x32_bf16 v[2:5], v[30:33], v[222:225], v[2:5]
	v_mfma_f32_16x16x32_bf16 v[78:81], v[38:41], v[166:169], v[78:81]
	v_mfma_f32_16x16x32_bf16 v[74:77], v[58:61], v[162:165], v[74:77]
	v_mfma_f32_16x16x32_bf16 v[70:73], v[38:41], v[186:189], v[70:73]
	v_mfma_f32_16x16x32_bf16 v[62:65], v[58:61], v[182:185], v[62:65]
	v_mfma_f32_16x16x32_bf16 v[54:57], v[38:41], v[206:209], v[54:57]
	v_mfma_f32_16x16x32_bf16 v[46:49], v[58:61], v[202:205], v[46:49]
	v_mfma_f32_16x16x32_bf16 v[38:41], v[38:41], v[226:229], v[2:5]
	v_mfma_f32_16x16x32_bf16 v[2:5], v[58:61], v[222:225], v[6:9]
	v_mfma_f32_16x16x32_bf16 v[74:77], v[66:69], v[166:169], v[74:77]
	v_mfma_f32_16x16x32_bf16 v[62:65], v[66:69], v[186:189], v[62:65]
	v_mfma_f32_16x16x32_bf16 v[46:49], v[66:69], v[206:209], v[46:49]
	v_mfma_f32_16x16x32_bf16 v[30:33], v[66:69], v[226:229], v[2:5]
	s_setprio 0
	s_setprio 1
	v_mfma_f32_16x16x32_bf16 v[2:5], v[146:149], v[162:165], v[10:13]
	v_mfma_f32_16x16x32_bf16 v[66:69], v[150:153], v[166:169], v[2:5]
	v_mfma_f32_16x16x32_bf16 v[2:5], v[154:157], v[162:165], v[14:17]
	v_mfma_f32_16x16x32_bf16 v[58:61], v[158:161], v[166:169], v[2:5]
	v_mfma_f32_16x16x32_bf16 v[2:5], v[146:149], v[182:185], v[50:53]
	v_mfma_f32_16x16x32_bf16 v[50:53], v[150:153], v[186:189], v[2:5]
	v_mfma_f32_16x16x32_bf16 v[2:5], v[154:157], v[182:185], v[42:45]
	v_mfma_f32_16x16x32_bf16 v[42:45], v[158:161], v[186:189], v[2:5]
	v_mfma_f32_16x16x32_bf16 v[2:5], v[146:149], v[202:205], v[34:37]
	v_mfma_f32_16x16x32_bf16 v[34:37], v[150:153], v[206:209], v[2:5]
	v_mfma_f32_16x16x32_bf16 v[2:5], v[154:157], v[202:205], v[26:29]
	s_setprio 3
	s_barrier
	v_mfma_f32_16x16x32_bf16 v[26:29], v[158:161], v[206:209], v[2:5]
	v_mfma_f32_16x16x32_bf16 v[2:5], v[146:149], v[222:225], v[22:25]
	v_mfma_f32_16x16x32_bf16 v[22:25], v[150:153], v[226:229], v[2:5]
	v_mfma_f32_16x16x32_bf16 v[2:5], v[154:157], v[222:225], v[18:21]
	v_mfma_f32_16x16x32_bf16 v[18:21], v[158:161], v[226:229], v[2:5]
	s_setprio 0
	s_add_i32 s17, s17, 2
	s_add_u32 s0, s0, 0x100
	s_addc_u32 s1, s1, 0
	s_add_u32 s14, s14, 0x100
	s_addc_u32 s15, s15, 0
	s_cmp_gt_u32 s17, 13
	s_cbranch_scc0 .LBB0_233
	s_and_b64 vcc, exec, s[78:79]
	s_cbranch_vccz .LBB0_236
	s_barrier

.LBB0_707:
	s_add_i32 s34, s68, 2
	s_add_u32 s35, s0, 0x80
	s_addc_u32 s69, s1, 0
	s_add_i32 s84, 0, 0x10000
	s_cmp_eq_u32 s96, s68
	s_cselect_b32 s69, s53, s69
	s_cselect_b32 s68, s52, s35
	s_cselect_b32 s89, s65, vcc_hi
	s_cselect_b32 s88, s64, vcc_lo
	s_add_i32 s35, 0, 0x14000
	v_add_u32_e32 v142, s84, v212
	v_add_u32_e32 v158, s35, v212
	ds_read_b128 v[130:133], v142
	ds_read_b128 v[134:137], v142 offset:1024
	ds_read_b128 v[138:141], v142 offset:2048
	ds_read_b128 v[142:145], v142 offset:3072
	ds_read_b128 v[146:149], v158
	ds_read_b128 v[150:153], v158 offset:1024
	ds_read_b128 v[154:157], v158 offset:2048
	ds_read_b128 v[158:161], v158 offset:3072
	v_lshl_add_u64 v[194:195], s[0:1], 0, v[224:225]
	s_add_i32 m0, s28, 0xc000
	ds_read_b128 v[162:165], v245
	ds_read_b128 v[166:169], v245 offset:1024
	ds_read_b128 v[170:173], v245 offset:2048
	ds_read_b128 v[174:177], v245 offset:3072
	ds_read_b128 v[178:181], v245 offset:4096
	ds_read_b128 v[182:185], v245 offset:5120
	ds_read_b128 v[186:189], v245 offset:6144
	ds_read_b128 v[190:193], v245 offset:7168
	global_load_lds_dwordx4 v[194:195], off
	v_lshl_add_u64 v[194:195], s[0:1], 0, v[226:227]
	s_add_i32 m0, s28, 0xe000
	s_nop 0
	global_load_lds_dwordx4 v[194:195], off
	s_waitcnt vmcnt(8)
	s_waitcnt lgkmcnt(0)
	s_barrier
	s_setprio 1
	s_waitcnt lgkmcnt(0)
	v_mfma_f32_16x16x32_bf16 v[126:129], v[130:133], v[162:165], v[126:129]
	v_mfma_f32_16x16x32_bf16 v[126:129], v[134:137], v[166:169], v[126:129]
	v_mfma_f32_16x16x32_bf16 v[122:125], v[138:141], v[162:165], v[122:125]
	v_mfma_f32_16x16x32_bf16 v[122:125], v[142:145], v[166:169], v[122:125]
	v_mfma_f32_16x16x32_bf16 v[114:117], v[130:133], v[170:173], v[114:117]
	v_mfma_f32_16x16x32_bf16 v[114:117], v[134:137], v[174:177], v[114:117]
	v_mfma_f32_16x16x32_bf16 v[106:109], v[138:141], v[170:173], v[106:109]
	v_mfma_f32_16x16x32_bf16 v[106:109], v[142:145], v[174:177], v[106:109]
	v_mfma_f32_16x16x32_bf16 v[98:101], v[130:133], v[178:181], v[98:101]
	v_mfma_f32_16x16x32_bf16 v[98:101], v[134:137], v[182:185], v[98:101]
	v_mfma_f32_16x16x32_bf16 v[90:93], v[138:141], v[178:181], v[90:93]
	v_mfma_f32_16x16x32_bf16 v[90:93], v[142:145], v[182:185], v[90:93]
	v_mfma_f32_16x16x32_bf16 v[82:85], v[130:133], v[186:189], v[82:85]
	v_mfma_f32_16x16x32_bf16 v[82:85], v[134:137], v[190:193], v[82:85]
	v_mfma_f32_16x16x32_bf16 v[74:77], v[138:141], v[186:189], v[74:77]
	v_mfma_f32_16x16x32_bf16 v[74:77], v[142:145], v[190:193], v[74:77]
	s_setprio 0
	s_setprio 1
	v_mfma_f32_16x16x32_bf16 v[118:121], v[146:149], v[162:165], v[118:121]
	v_mfma_f32_16x16x32_bf16 v[118:121], v[150:153], v[166:169], v[118:121]
	v_mfma_f32_16x16x32_bf16 v[110:113], v[154:157], v[162:165], v[110:113]
	v_mfma_f32_16x16x32_bf16 v[110:113], v[158:161], v[166:169], v[110:113]
	v_mfma_f32_16x16x32_bf16 v[102:105], v[146:149], v[170:173], v[102:105]
	v_mfma_f32_16x16x32_bf16 v[102:105], v[150:153], v[174:177], v[102:105]
	v_mfma_f32_16x16x32_bf16 v[94:97], v[154:157], v[170:173], v[94:97]
	v_mfma_f32_16x16x32_bf16 v[94:97], v[158:161], v[174:177], v[94:97]
	v_mfma_f32_16x16x32_bf16 v[86:89], v[146:149], v[178:181], v[86:89]
	v_mfma_f32_16x16x32_bf16 v[86:89], v[150:153], v[182:185], v[86:89]
	v_mfma_f32_16x16x32_bf16 v[78:81], v[154:157], v[178:181], v[78:81]
	s_setprio 3
	s_barrier
	v_mfma_f32_16x16x32_bf16 v[78:81], v[158:161], v[182:185], v[78:81]
	v_mfma_f32_16x16x32_bf16 v[70:73], v[146:149], v[186:189], v[70:73]
	v_mfma_f32_16x16x32_bf16 v[70:73], v[150:153], v[190:193], v[70:73]
	v_mfma_f32_16x16x32_bf16 v[66:69], v[154:157], v[186:189], v[66:69]
	v_mfma_f32_16x16x32_bf16 v[66:69], v[158:161], v[190:193], v[66:69]
	s_setprio 0
	s_add_i32 s84, s84, s19
	s_add_u32 s98, s88, s22
	s_addc_u32 s99, s89, s23
	s_mov_b32 m0, s84
	ds_read_b128 v[162:165], v245 offset:16384
	ds_read_b128 v[166:169], v245 offset:17408
	ds_read_b128 v[170:173], v245 offset:18432
	ds_read_b128 v[174:177], v245 offset:19456
	ds_read_b128 v[178:181], v245 offset:20480
	ds_read_b128 v[182:185], v245 offset:21504
	ds_read_b128 v[186:189], v245 offset:22528
	ds_read_b128 v[190:193], v245 offset:23552
	global_load_lds_dwordx4 v0, s[88:89]
	s_add_i32 m0, s84, 0x2000
	s_add_i32 s35, s35, s19
	global_load_lds_dwordx4 v222, s[88:89]
	s_add_u32 s88, s88, s2
	s_addc_u32 s89, s89, 0
	s_mov_b32 m0, s35
	s_nop 0
	global_load_lds_dwordx4 v0, s[88:89]
	s_add_i32 m0, s35, 0x2000
	s_add_u32 s100, s68, s22
	s_addc_u32 s101, s69, s23
	global_load_lds_dwordx4 v222, s[88:89]
	s_mov_b32 m0, s28
	s_nop 0
	global_load_lds_dwordx4 v0, s[68:69]
	s_mov_b32 m0, s29
	s_nop 0
	global_load_lds_dwordx4 v222, s[68:69]
	s_waitcnt vmcnt(8)
	s_waitcnt lgkmcnt(0)
	s_barrier
	s_setprio 1
	s_waitcnt lgkmcnt(0)
	v_mfma_f32_16x16x32_bf16 v[62:65], v[130:133], v[162:165], v[62:65]
	v_mfma_f32_16x16x32_bf16 v[62:65], v[134:137], v[166:169], v[62:65]
	v_mfma_f32_16x16x32_bf16 v[58:61], v[138:141], v[162:165], v[58:61]
	v_mfma_f32_16x16x32_bf16 v[58:61], v[142:145], v[166:169], v[58:61]
	v_mfma_f32_16x16x32_bf16 v[50:53], v[130:133], v[170:173], v[50:53]
	v_mfma_f32_16x16x32_bf16 v[50:53], v[134:137], v[174:177], v[50:53]
	v_mfma_f32_16x16x32_bf16 v[42:45], v[138:141], v[170:173], v[42:45]
	v_mfma_f32_16x16x32_bf16 v[42:45], v[142:145], v[174:177], v[42:45]
	v_mfma_f32_16x16x32_bf16 v[34:37], v[130:133], v[178:181], v[34:37]
	v_mfma_f32_16x16x32_bf16 v[34:37], v[134:137], v[182:185], v[34:37]
	v_mfma_f32_16x16x32_bf16 v[26:29], v[138:141], v[178:181], v[26:29]
	v_mfma_f32_16x16x32_bf16 v[26:29], v[142:145], v[182:185], v[26:29]
	v_mfma_f32_16x16x32_bf16 v[18:21], v[130:133], v[186:189], v[18:21]
	v_mfma_f32_16x16x32_bf16 v[18:21], v[134:137], v[190:193], v[18:21]
	v_mfma_f32_16x16x32_bf16 v[10:13], v[138:141], v[186:189], v[10:13]
	v_mfma_f32_16x16x32_bf16 v[10:13], v[142:145], v[190:193], v[10:13]
	s_setprio 0
	s_setprio 1
	v_mfma_f32_16x16x32_bf16 v[54:57], v[146:149], v[162:165], v[54:57]
	v_mfma_f32_16x16x32_bf16 v[54:57], v[150:153], v[166:169], v[54:57]
	v_mfma_f32_16x16x32_bf16 v[46:49], v[154:157], v[162:165], v[46:49]
	v_mfma_f32_16x16x32_bf16 v[46:49], v[158:161], v[166:169], v[46:49]
	v_mfma_f32_16x16x32_bf16 v[38:41], v[146:149], v[170:173], v[38:41]
	v_mfma_f32_16x16x32_bf16 v[38:41], v[150:153], v[174:177], v[38:41]
	v_mfma_f32_16x16x32_bf16 v[30:33], v[154:157], v[170:173], v[30:33]
	v_mfma_f32_16x16x32_bf16 v[30:33], v[158:161], v[174:177], v[30:33]
	v_mfma_f32_16x16x32_bf16 v[22:25], v[146:149], v[178:181], v[22:25]
	v_mfma_f32_16x16x32_bf16 v[22:25], v[150:153], v[182:185], v[22:25]
	v_mfma_f32_16x16x32_bf16 v[14:17], v[154:157], v[178:181], v[14:17]
	s_setprio 3
	s_barrier
	v_mfma_f32_16x16x32_bf16 v[14:17], v[158:161], v[182:185], v[14:17]
	v_mfma_f32_16x16x32_bf16 v[6:9], v[146:149], v[186:189], v[6:9]
	v_mfma_f32_16x16x32_bf16 v[6:9], v[150:153], v[190:193], v[6:9]
	v_mfma_f32_16x16x32_bf16 v[2:5], v[154:157], v[186:189], v[2:5]
	v_mfma_f32_16x16x32_bf16 v[2:5], v[158:161], v[190:193], v[2:5]
	s_setprio 0
	s_add_i32 s35, 0, 0x18000
	s_add_i32 s84, 0, 0x1c000
	v_add_u32_e32 v142, s35, v212
	v_add_u32_e32 v158, s84, v212
	ds_read_b128 v[130:133], v142
	ds_read_b128 v[134:137], v142 offset:1024
	ds_read_b128 v[138:141], v142 offset:2048
	ds_read_b128 v[142:145], v142 offset:3072
	ds_read_b128 v[146:149], v158
	ds_read_b128 v[150:153], v158 offset:1024
	ds_read_b128 v[154:157], v158 offset:2048
	ds_read_b128 v[158:161], v158 offset:3072
	s_add_u32 s68, s68, s2
	s_addc_u32 s69, s69, 0
	s_mov_b32 m0, s25
	ds_read_b128 v[162:165], v245 offset:32768
	ds_read_b128 v[166:169], v245 offset:33792
	ds_read_b128 v[170:173], v245 offset:34816
	ds_read_b128 v[174:177], v245 offset:35840
	ds_read_b128 v[178:181], v245 offset:36864
	ds_read_b128 v[182:185], v245 offset:37888
	ds_read_b128 v[186:189], v245 offset:38912
	ds_read_b128 v[190:193], v245 offset:39936
	global_load_lds_dwordx4 v0, s[68:69]
	s_mov_b32 m0, s36
	s_nop 0
	global_load_lds_dwordx4 v222, s[68:69]
	s_waitcnt vmcnt(8)
	s_waitcnt lgkmcnt(0)
	s_barrier
	s_setprio 1
	s_waitcnt lgkmcnt(0)
	v_mfma_f32_16x16x32_bf16 v[126:129], v[130:133], v[162:165], v[126:129]
	v_mfma_f32_16x16x32_bf16 v[126:129], v[134:137], v[166:169], v[126:129]
	v_mfma_f32_16x16x32_bf16 v[122:125], v[138:141], v[162:165], v[122:125]
	v_mfma_f32_16x16x32_bf16 v[122:125], v[142:145], v[166:169], v[122:125]
	v_mfma_f32_16x16x32_bf16 v[114:117], v[130:133], v[170:173], v[114:117]
	v_mfma_f32_16x16x32_bf16 v[114:117], v[134:137], v[174:177], v[114:117]
	v_mfma_f32_16x16x32_bf16 v[106:109], v[138:141], v[170:173], v[106:109]
	v_mfma_f32_16x16x32_bf16 v[106:109], v[142:145], v[174:177], v[106:109]
	v_mfma_f32_16x16x32_bf16 v[98:101], v[130:133], v[178:181], v[98:101]
	v_mfma_f32_16x16x32_bf16 v[98:101], v[134:137], v[182:185], v[98:101]
	v_mfma_f32_16x16x32_bf16 v[90:93], v[138:141], v[178:181], v[90:93]
	v_mfma_f32_16x16x32_bf16 v[90:93], v[142:145], v[182:185], v[90:93]
	v_mfma_f32_16x16x32_bf16 v[82:85], v[130:133], v[186:189], v[82:85]
	v_mfma_f32_16x16x32_bf16 v[82:85], v[134:137], v[190:193], v[82:85]
	v_mfma_f32_16x16x32_bf16 v[74:77], v[138:141], v[186:189], v[74:77]
	v_mfma_f32_16x16x32_bf16 v[74:77], v[142:145], v[190:193], v[74:77]
	s_setprio 0
	s_setprio 1
	v_mfma_f32_16x16x32_bf16 v[118:121], v[146:149], v[162:165], v[118:121]
	v_mfma_f32_16x16x32_bf16 v[118:121], v[150:153], v[166:169], v[118:121]
	v_mfma_f32_16x16x32_bf16 v[110:113], v[154:157], v[162:165], v[110:113]
	v_mfma_f32_16x16x32_bf16 v[110:113], v[158:161], v[166:169], v[110:113]
	v_mfma_f32_16x16x32_bf16 v[102:105], v[146:149], v[170:173], v[102:105]
	v_mfma_f32_16x16x32_bf16 v[102:105], v[150:153], v[174:177], v[102:105]
	v_mfma_f32_16x16x32_bf16 v[94:97], v[154:157], v[170:173], v[94:97]
	v_mfma_f32_16x16x32_bf16 v[94:97], v[158:161], v[174:177], v[94:97]
	v_mfma_f32_16x16x32_bf16 v[86:89], v[146:149], v[178:181], v[86:89]
	v_mfma_f32_16x16x32_bf16 v[86:89], v[150:153], v[182:185], v[86:89]
	v_mfma_f32_16x16x32_bf16 v[78:81], v[154:157], v[178:181], v[78:81]
	s_setprio 3
	s_barrier
	v_mfma_f32_16x16x32_bf16 v[78:81], v[158:161], v[182:185], v[78:81]
	v_mfma_f32_16x16x32_bf16 v[70:73], v[146:149], v[186:189], v[70:73]
	v_mfma_f32_16x16x32_bf16 v[70:73], v[150:153], v[190:193], v[70:73]
	v_mfma_f32_16x16x32_bf16 v[66:69], v[154:157], v[186:189], v[66:69]
	v_mfma_f32_16x16x32_bf16 v[66:69], v[158:161], v[190:193], v[66:69]
	s_setprio 0
	s_add_i32 s35, s35, s19
	s_mov_b32 m0, s35
	ds_read_b128 v[162:165], v245 offset:49152
	ds_read_b128 v[166:169], v245 offset:50176
	ds_read_b128 v[170:173], v245 offset:51200
	ds_read_b128 v[174:177], v245 offset:52224
	ds_read_b128 v[178:181], v245 offset:53248
	ds_read_b128 v[182:185], v245 offset:54272
	ds_read_b128 v[186:189], v245 offset:55296
	ds_read_b128 v[190:193], v245 offset:56320
	global_load_lds_dwordx4 v0, s[98:99]
	s_add_i32 m0, s35, 0x2000
	s_add_i32 s35, s84, s19
	global_load_lds_dwordx4 v222, s[98:99]
	s_add_u32 s98, s98, s2
	s_addc_u32 s99, s99, 0
	s_mov_b32 m0, s35
	s_nop 0
	global_load_lds_dwordx4 v0, s[98:99]
	s_add_i32 m0, s35, 0x2000
	s_nop 0
	global_load_lds_dwordx4 v222, s[98:99]
	s_mov_b32 m0, s37
	s_nop 0
	global_load_lds_dwordx4 v0, s[100:101]
	s_mov_b32 m0, s40
	s_nop 0
	global_load_lds_dwordx4 v222, s[100:101]
	s_waitcnt vmcnt(8)
	s_waitcnt lgkmcnt(0)
	s_barrier
	s_setprio 1
	s_waitcnt lgkmcnt(0)
	v_mfma_f32_16x16x32_bf16 v[62:65], v[130:133], v[162:165], v[62:65]
	v_mfma_f32_16x16x32_bf16 v[62:65], v[134:137], v[166:169], v[62:65]
	v_mfma_f32_16x16x32_bf16 v[58:61], v[138:141], v[162:165], v[58:61]
	v_mfma_f32_16x16x32_bf16 v[58:61], v[142:145], v[166:169], v[58:61]
	v_mfma_f32_16x16x32_bf16 v[50:53], v[130:133], v[170:173], v[50:53]
	v_mfma_f32_16x16x32_bf16 v[50:53], v[134:137], v[174:177], v[50:53]
	v_mfma_f32_16x16x32_bf16 v[42:45], v[138:141], v[170:173], v[42:45]
	v_mfma_f32_16x16x32_bf16 v[42:45], v[142:145], v[174:177], v[42:45]
	v_mfma_f32_16x16x32_bf16 v[34:37], v[130:133], v[178:181], v[34:37]
	v_mfma_f32_16x16x32_bf16 v[34:37], v[134:137], v[182:185], v[34:37]
	v_mfma_f32_16x16x32_bf16 v[26:29], v[138:141], v[178:181], v[26:29]
	v_mfma_f32_16x16x32_bf16 v[26:29], v[142:145], v[182:185], v[26:29]
	v_mfma_f32_16x16x32_bf16 v[18:21], v[130:133], v[186:189], v[18:21]
	v_mfma_f32_16x16x32_bf16 v[18:21], v[134:137], v[190:193], v[18:21]
	v_mfma_f32_16x16x32_bf16 v[10:13], v[138:141], v[186:189], v[10:13]
	v_mfma_f32_16x16x32_bf16 v[10:13], v[142:145], v[190:193], v[10:13]
	s_setprio 0
	s_setprio 1
	v_mfma_f32_16x16x32_bf16 v[54:57], v[146:149], v[162:165], v[54:57]
	v_mfma_f32_16x16x32_bf16 v[54:57], v[150:153], v[166:169], v[54:57]
	v_mfma_f32_16x16x32_bf16 v[46:49], v[154:157], v[162:165], v[46:49]
	v_mfma_f32_16x16x32_bf16 v[46:49], v[158:161], v[166:169], v[46:49]
	v_mfma_f32_16x16x32_bf16 v[38:41], v[146:149], v[170:173], v[38:41]
	v_mfma_f32_16x16x32_bf16 v[38:41], v[150:153], v[174:177], v[38:41]
	v_mfma_f32_16x16x32_bf16 v[30:33], v[154:157], v[170:173], v[30:33]
	v_mfma_f32_16x16x32_bf16 v[30:33], v[158:161], v[174:177], v[30:33]
	v_mfma_f32_16x16x32_bf16 v[22:25], v[146:149], v[178:181], v[22:25]
	v_mfma_f32_16x16x32_bf16 v[22:25], v[150:153], v[182:185], v[22:25]
	v_mfma_f32_16x16x32_bf16 v[14:17], v[154:157], v[178:181], v[14:17]
	s_setprio 3
	s_barrier
	v_mfma_f32_16x16x32_bf16 v[14:17], v[158:161], v[182:185], v[14:17]
	v_mfma_f32_16x16x32_bf16 v[6:9], v[146:149], v[186:189], v[6:9]
	v_mfma_f32_16x16x32_bf16 v[6:9], v[150:153], v[190:193], v[6:9]
	v_mfma_f32_16x16x32_bf16 v[2:5], v[154:157], v[186:189], v[2:5]
	v_mfma_f32_16x16x32_bf16 v[2:5], v[158:161], v[190:193], v[2:5]
	s_setprio 0
	s_add_u32 s0, s0, 0x100
	s_addc_u32 s1, s1, 0
	s_add_u32 vcc_lo, vcc_lo, 0x100
	s_addc_u32 vcc_hi, vcc_hi, 0
	s_cmp_ge_u32 s34, s18
	s_mov_b32 s68, s34
	s_cbranch_scc0 .LBB0_707
	s_and_b64 vcc, exec, s[50:51]
	s_cbranch_vccz .LBB0_710
	s_barrier
